# in-proj epilogue: 8 LDS row reads in flight then 8 stores (was read-wait-store x8) for q/k/z/x_lru/z_lru tiles; k-tile key-norm reduction batched
# speedup vs baseline: 1.0098x; 1.0011x over previous
.LBB0_147:
	s_lshl_b32 s2, s88, 1
	s_add_u32 s0, s0, s2
	s_addc_u32 s1, s1, 0
	v_lshlrev_b32_e32 v132, 1, v143
	v_lshl_add_u64 v[138:139], s[0:1], 0, v[132:133]
	v_ashrrev_i32_e32 v251, 5, v135
	v_mad_u32_u24 v252, v251, s89, v134
	ds_read_b128 v[206:209], v252
	v_add_u32_e32 v250, 0x200, v135
	v_ashrrev_i32_e32 v251, 5, v250
	v_mad_u32_u24 v252, v251, s89, v134
	ds_read_b128 v[210:213], v252
	v_add_u32_e32 v250, 0x400, v135
	v_ashrrev_i32_e32 v251, 5, v250
	v_mad_u32_u24 v252, v251, s89, v134
	ds_read_b128 v[214:217], v252
	v_add_u32_e32 v250, 0x600, v135
	v_ashrrev_i32_e32 v251, 5, v250
	v_mad_u32_u24 v252, v251, s89, v134
	ds_read_b128 v[218:221], v252
	v_add_u32_e32 v250, 0x800, v135
	v_ashrrev_i32_e32 v251, 5, v250
	v_mad_u32_u24 v252, v251, s89, v134
	ds_read_b128 v[222:225], v252
	v_add_u32_e32 v250, 0xa00, v135
	v_ashrrev_i32_e32 v251, 5, v250
	v_mad_u32_u24 v252, v251, s89, v134
	ds_read_b128 v[226:229], v252
	v_add_u32_e32 v250, 0xc00, v135
	v_ashrrev_i32_e32 v251, 5, v250
	v_mad_u32_u24 v252, v251, s89, v134
	ds_read_b128 v[230:233], v252
	v_add_u32_e32 v250, 0xe00, v135
	v_ashrrev_i32_e32 v251, 5, v250
	v_mad_u32_u24 v252, v251, s89, v134
	ds_read_b128 v[234:237], v252
	v_ashrrev_i32_e32 v251, 5, v135
	v_add_u32_e32 v252, s97, v251
	v_ashrrev_i32_e32 v253, 31, v252
	v_lshlrev_b64 v[252:253], 11, v[252:253]
	v_lshl_add_u64 v[252:253], v[138:139], 0, v[252:253]
	s_waitcnt lgkmcnt(7)
	global_store_dwordx4 v[252:253], v[206:209], off
	v_add_u32_e32 v250, 0x200, v135
	v_ashrrev_i32_e32 v251, 5, v250
	v_add_u32_e32 v252, s97, v251
	v_ashrrev_i32_e32 v253, 31, v252
	v_lshlrev_b64 v[252:253], 11, v[252:253]
	v_lshl_add_u64 v[252:253], v[138:139], 0, v[252:253]
	s_waitcnt lgkmcnt(6)
	global_store_dwordx4 v[252:253], v[210:213], off
	v_add_u32_e32 v250, 0x400, v135
	v_ashrrev_i32_e32 v251, 5, v250
	v_add_u32_e32 v252, s97, v251
	v_ashrrev_i32_e32 v253, 31, v252
	v_lshlrev_b64 v[252:253], 11, v[252:253]
	v_lshl_add_u64 v[252:253], v[138:139], 0, v[252:253]
	s_waitcnt lgkmcnt(5)
	global_store_dwordx4 v[252:253], v[214:217], off
	v_add_u32_e32 v250, 0x600, v135
	v_ashrrev_i32_e32 v251, 5, v250
	v_add_u32_e32 v252, s97, v251
	v_ashrrev_i32_e32 v253, 31, v252
	v_lshlrev_b64 v[252:253], 11, v[252:253]
	v_lshl_add_u64 v[252:253], v[138:139], 0, v[252:253]
	s_waitcnt lgkmcnt(4)
	global_store_dwordx4 v[252:253], v[218:221], off
	v_add_u32_e32 v250, 0x800, v135
	v_ashrrev_i32_e32 v251, 5, v250
	v_add_u32_e32 v252, s97, v251
	v_ashrrev_i32_e32 v253, 31, v252
	v_lshlrev_b64 v[252:253], 11, v[252:253]
	v_lshl_add_u64 v[252:253], v[138:139], 0, v[252:253]
	s_waitcnt lgkmcnt(3)
	global_store_dwordx4 v[252:253], v[222:225], off
	v_add_u32_e32 v250, 0xa00, v135
	v_ashrrev_i32_e32 v251, 5, v250
	v_add_u32_e32 v252, s97, v251
	v_ashrrev_i32_e32 v253, 31, v252
	v_lshlrev_b64 v[252:253], 11, v[252:253]
	v_lshl_add_u64 v[252:253], v[138:139], 0, v[252:253]
	s_waitcnt lgkmcnt(2)
	global_store_dwordx4 v[252:253], v[226:229], off
	v_add_u32_e32 v250, 0xc00, v135
	v_ashrrev_i32_e32 v251, 5, v250
	v_add_u32_e32 v252, s97, v251
	v_ashrrev_i32_e32 v253, 31, v252
	v_lshlrev_b64 v[252:253], 11, v[252:253]
	v_lshl_add_u64 v[252:253], v[138:139], 0, v[252:253]
	s_waitcnt lgkmcnt(1)
	global_store_dwordx4 v[252:253], v[230:233], off
	v_add_u32_e32 v250, 0xe00, v135
	v_ashrrev_i32_e32 v251, 5, v250
	v_add_u32_e32 v252, s97, v251
	v_ashrrev_i32_e32 v253, 31, v252
	v_lshlrev_b64 v[252:253], 11, v[252:253]
	v_lshl_add_u64 v[252:253], v[138:139], 0, v[252:253]
	s_waitcnt lgkmcnt(0)
	global_store_dwordx4 v[252:253], v[234:237], off
	v_mov_b32_e32 v137, 0
	s_and_b64 vcc, exec, s[28:29]
	s_cbranch_vccz .LBB0_163
	v_xor_b32_e32 v246, 1, v188
	v_lshlrev_b32_e32 v246, 2, v246
	v_xor_b32_e32 v247, 2, v188
	v_lshlrev_b32_e32 v247, 2, v247
	v_xor_b32_e32 v248, 4, v188
	v_lshlrev_b32_e32 v248, 2, v248
	v_xor_b32_e32 v249, 8, v188
	v_lshlrev_b32_e32 v249, 2, v249
	v_lshlrev_b32_e32 v251, 16, v207
	v_lshlrev_b32_e32 v250, 16, v206
	v_and_b32_e32 v207, 0xffff0000, v207
	v_and_b32_e32 v206, 0xffff0000, v206
	v_pk_mul_f32 v[206:207], v[206:207], v[206:207]
	s_nop 0
	v_pk_fma_f32 v[206:207], v[250:251], v[250:251], v[206:207]
	v_lshlrev_b32_e32 v251, 16, v209
	v_lshlrev_b32_e32 v250, 16, v208
	v_and_b32_e32 v209, 0xffff0000, v209
	v_and_b32_e32 v208, 0xffff0000, v208
	v_pk_mul_f32 v[208:209], v[208:209], v[208:209]
	s_nop 0
	v_pk_fma_f32 v[208:209], v[250:251], v[250:251], v[208:209]
	v_add_f32_e32 v206, v206, v207
	v_add_f32_e32 v206, v208, v206
	v_add_f32_e32 v206, v209, v206
	v_lshlrev_b32_e32 v251, 16, v211
	v_lshlrev_b32_e32 v250, 16, v210
	v_and_b32_e32 v211, 0xffff0000, v211
	v_and_b32_e32 v210, 0xffff0000, v210
	v_pk_mul_f32 v[210:211], v[210:211], v[210:211]
	s_nop 0
	v_pk_fma_f32 v[210:211], v[250:251], v[250:251], v[210:211]
	v_lshlrev_b32_e32 v251, 16, v213
	v_lshlrev_b32_e32 v250, 16, v212
	v_and_b32_e32 v213, 0xffff0000, v213
	v_and_b32_e32 v212, 0xffff0000, v212
	v_pk_mul_f32 v[212:213], v[212:213], v[212:213]
	s_nop 0
	v_pk_fma_f32 v[212:213], v[250:251], v[250:251], v[212:213]
	v_add_f32_e32 v210, v210, v211
	v_add_f32_e32 v210, v212, v210
	v_add_f32_e32 v210, v213, v210
	v_lshlrev_b32_e32 v251, 16, v215
	v_lshlrev_b32_e32 v250, 16, v214
	v_and_b32_e32 v215, 0xffff0000, v215
	v_and_b32_e32 v214, 0xffff0000, v214
	v_pk_mul_f32 v[214:215], v[214:215], v[214:215]
	s_nop 0
	v_pk_fma_f32 v[214:215], v[250:251], v[250:251], v[214:215]
	v_lshlrev_b32_e32 v251, 16, v217
	v_lshlrev_b32_e32 v250, 16, v216
	v_and_b32_e32 v217, 0xffff0000, v217
	v_and_b32_e32 v216, 0xffff0000, v216
	v_pk_mul_f32 v[216:217], v[216:217], v[216:217]
	s_nop 0
	v_pk_fma_f32 v[216:217], v[250:251], v[250:251], v[216:217]
	v_add_f32_e32 v214, v214, v215
	v_add_f32_e32 v214, v216, v214
	v_add_f32_e32 v214, v217, v214
	v_lshlrev_b32_e32 v251, 16, v219
	v_lshlrev_b32_e32 v250, 16, v218
	v_and_b32_e32 v219, 0xffff0000, v219
	v_and_b32_e32 v218, 0xffff0000, v218
	v_pk_mul_f32 v[218:219], v[218:219], v[218:219]
	s_nop 0
	v_pk_fma_f32 v[218:219], v[250:251], v[250:251], v[218:219]
	v_lshlrev_b32_e32 v251, 16, v221
	v_lshlrev_b32_e32 v250, 16, v220
	v_and_b32_e32 v221, 0xffff0000, v221
	v_and_b32_e32 v220, 0xffff0000, v220
	v_pk_mul_f32 v[220:221], v[220:221], v[220:221]
	s_nop 0
	v_pk_fma_f32 v[220:221], v[250:251], v[250:251], v[220:221]
	v_add_f32_e32 v218, v218, v219
	v_add_f32_e32 v218, v220, v218
	v_add_f32_e32 v218, v221, v218
	v_lshlrev_b32_e32 v251, 16, v223
	v_lshlrev_b32_e32 v250, 16, v222
	v_and_b32_e32 v223, 0xffff0000, v223
	v_and_b32_e32 v222, 0xffff0000, v222
	v_pk_mul_f32 v[222:223], v[222:223], v[222:223]
	s_nop 0
	v_pk_fma_f32 v[222:223], v[250:251], v[250:251], v[222:223]
	v_lshlrev_b32_e32 v251, 16, v225
	v_lshlrev_b32_e32 v250, 16, v224
	v_and_b32_e32 v225, 0xffff0000, v225
	v_and_b32_e32 v224, 0xffff0000, v224
	v_pk_mul_f32 v[224:225], v[224:225], v[224:225]
	s_nop 0
	v_pk_fma_f32 v[224:225], v[250:251], v[250:251], v[224:225]
	v_add_f32_e32 v222, v222, v223
	v_add_f32_e32 v222, v224, v222
	v_add_f32_e32 v222, v225, v222
	v_lshlrev_b32_e32 v251, 16, v227
	v_lshlrev_b32_e32 v250, 16, v226
	v_and_b32_e32 v227, 0xffff0000, v227
	v_and_b32_e32 v226, 0xffff0000, v226
	v_pk_mul_f32 v[226:227], v[226:227], v[226:227]
	s_nop 0
	v_pk_fma_f32 v[226:227], v[250:251], v[250:251], v[226:227]
	v_lshlrev_b32_e32 v251, 16, v229
	v_lshlrev_b32_e32 v250, 16, v228
	v_and_b32_e32 v229, 0xffff0000, v229
	v_and_b32_e32 v228, 0xffff0000, v228
	v_pk_mul_f32 v[228:229], v[228:229], v[228:229]
	s_nop 0
	v_pk_fma_f32 v[228:229], v[250:251], v[250:251], v[228:229]
	v_add_f32_e32 v226, v226, v227
	v_add_f32_e32 v226, v228, v226
	v_add_f32_e32 v226, v229, v226
	v_lshlrev_b32_e32 v251, 16, v231
	v_lshlrev_b32_e32 v250, 16, v230
	v_and_b32_e32 v231, 0xffff0000, v231
	v_and_b32_e32 v230, 0xffff0000, v230
	v_pk_mul_f32 v[230:231], v[230:231], v[230:231]
	s_nop 0
	v_pk_fma_f32 v[230:231], v[250:251], v[250:251], v[230:231]
	v_lshlrev_b32_e32 v251, 16, v233
	v_lshlrev_b32_e32 v250, 16, v232
	v_and_b32_e32 v233, 0xffff0000, v233
	v_and_b32_e32 v232, 0xffff0000, v232
	v_pk_mul_f32 v[232:233], v[232:233], v[232:233]
	s_nop 0
	v_pk_fma_f32 v[232:233], v[250:251], v[250:251], v[232:233]
	v_add_f32_e32 v230, v230, v231
	v_add_f32_e32 v230, v232, v230
	v_add_f32_e32 v230, v233, v230
	v_lshlrev_b32_e32 v251, 16, v235
	v_lshlrev_b32_e32 v250, 16, v234
	v_and_b32_e32 v235, 0xffff0000, v235
	v_and_b32_e32 v234, 0xffff0000, v234
	v_pk_mul_f32 v[234:235], v[234:235], v[234:235]
	s_nop 0
	v_pk_fma_f32 v[234:235], v[250:251], v[250:251], v[234:235]
	v_lshlrev_b32_e32 v251, 16, v237
	v_lshlrev_b32_e32 v250, 16, v236
	v_and_b32_e32 v237, 0xffff0000, v237
	v_and_b32_e32 v236, 0xffff0000, v236
	v_pk_mul_f32 v[236:237], v[236:237], v[236:237]
	s_nop 0
	v_pk_fma_f32 v[236:237], v[250:251], v[250:251], v[236:237]
	v_add_f32_e32 v234, v234, v235
	v_add_f32_e32 v234, v236, v234
	v_add_f32_e32 v234, v237, v234
	ds_bpermute_b32 v238, v246, v206
	ds_bpermute_b32 v239, v246, v210
	ds_bpermute_b32 v240, v246, v214
	ds_bpermute_b32 v241, v246, v218
	ds_bpermute_b32 v242, v246, v222
	ds_bpermute_b32 v243, v246, v226
	ds_bpermute_b32 v244, v246, v230
	ds_bpermute_b32 v245, v246, v234
	s_waitcnt lgkmcnt(7)
	v_add_f32_e32 v206, v206, v238
	s_waitcnt lgkmcnt(6)
	v_add_f32_e32 v210, v210, v239
	s_waitcnt lgkmcnt(5)
	v_add_f32_e32 v214, v214, v240
	s_waitcnt lgkmcnt(4)
	v_add_f32_e32 v218, v218, v241
	s_waitcnt lgkmcnt(3)
	v_add_f32_e32 v222, v222, v242
	s_waitcnt lgkmcnt(2)
	v_add_f32_e32 v226, v226, v243
	s_waitcnt lgkmcnt(1)
	v_add_f32_e32 v230, v230, v244
	s_waitcnt lgkmcnt(0)
	v_add_f32_e32 v234, v234, v245
	ds_bpermute_b32 v238, v247, v206
	ds_bpermute_b32 v239, v247, v210
	ds_bpermute_b32 v240, v247, v214
	ds_bpermute_b32 v241, v247, v218
	ds_bpermute_b32 v242, v247, v222
	ds_bpermute_b32 v243, v247, v226
	ds_bpermute_b32 v244, v247, v230
	ds_bpermute_b32 v245, v247, v234
	s_waitcnt lgkmcnt(7)
	v_add_f32_e32 v206, v206, v238
	s_waitcnt lgkmcnt(6)
	v_add_f32_e32 v210, v210, v239
	s_waitcnt lgkmcnt(5)
	v_add_f32_e32 v214, v214, v240
	s_waitcnt lgkmcnt(4)
	v_add_f32_e32 v218, v218, v241
	s_waitcnt lgkmcnt(3)
	v_add_f32_e32 v222, v222, v242
	s_waitcnt lgkmcnt(2)
	v_add_f32_e32 v226, v226, v243
	s_waitcnt lgkmcnt(1)
	v_add_f32_e32 v230, v230, v244
	s_waitcnt lgkmcnt(0)
	v_add_f32_e32 v234, v234, v245
	ds_bpermute_b32 v238, v248, v206
	ds_bpermute_b32 v239, v248, v210
	ds_bpermute_b32 v240, v248, v214
	ds_bpermute_b32 v241, v248, v218
	ds_bpermute_b32 v242, v248, v222
	ds_bpermute_b32 v243, v248, v226
	ds_bpermute_b32 v244, v248, v230
	ds_bpermute_b32 v245, v248, v234
	s_waitcnt lgkmcnt(7)
	v_add_f32_e32 v206, v206, v238
	s_waitcnt lgkmcnt(6)
	v_add_f32_e32 v210, v210, v239
	s_waitcnt lgkmcnt(5)
	v_add_f32_e32 v214, v214, v240
	s_waitcnt lgkmcnt(4)
	v_add_f32_e32 v218, v218, v241
	s_waitcnt lgkmcnt(3)
	v_add_f32_e32 v222, v222, v242
	s_waitcnt lgkmcnt(2)
	v_add_f32_e32 v226, v226, v243
	s_waitcnt lgkmcnt(1)
	v_add_f32_e32 v230, v230, v244
	s_waitcnt lgkmcnt(0)
	v_add_f32_e32 v234, v234, v245
	ds_bpermute_b32 v238, v249, v206
	ds_bpermute_b32 v239, v249, v210
	ds_bpermute_b32 v240, v249, v214
	ds_bpermute_b32 v241, v249, v218
	ds_bpermute_b32 v242, v249, v222
	ds_bpermute_b32 v243, v249, v226
	ds_bpermute_b32 v244, v249, v230
	ds_bpermute_b32 v245, v249, v234
	s_waitcnt lgkmcnt(7)
	v_add_f32_e32 v206, v206, v238
	s_waitcnt lgkmcnt(6)
	v_add_f32_e32 v210, v210, v239
	s_waitcnt lgkmcnt(5)
	v_add_f32_e32 v214, v214, v240
	s_waitcnt lgkmcnt(4)
	v_add_f32_e32 v218, v218, v241
	s_waitcnt lgkmcnt(3)
	v_add_f32_e32 v222, v222, v242
	s_waitcnt lgkmcnt(2)
	v_add_f32_e32 v226, v226, v243
	s_waitcnt lgkmcnt(1)
	v_add_f32_e32 v230, v230, v244
	s_waitcnt lgkmcnt(0)
	v_add_f32_e32 v234, v234, v245
	v_max_f32_e32 v137, 0, v206
	v_max_f32_e32 v250, v137, v137
	v_max_f32_e32 v137, v250, v210
	v_max_f32_e32 v250, v137, v137
	v_max_f32_e32 v137, v250, v214
	v_max_f32_e32 v250, v137, v137
	v_max_f32_e32 v137, v250, v218
	v_max_f32_e32 v250, v137, v137
	v_max_f32_e32 v137, v250, v222
	v_max_f32_e32 v250, v137, v137
	v_max_f32_e32 v137, v250, v226
	v_max_f32_e32 v250, v137, v137
	v_max_f32_e32 v137, v250, v230
	v_max_f32_e32 v250, v137, v137
	v_max_f32_e32 v137, v250, v234

.LBB0_177:
	s_bitset1_b32 s97, 7
	s_lshl_b32 s4, s88, 1
	s_add_u32 s0, s0, s4
	s_addc_u32 s1, s1, 0
	v_lshlrev_b32_e32 v132, 1, v143
	v_ashrrev_i32_e32 v70, 5, v135
	v_lshl_add_u64 v[68:69], s[0:1], 0, v[132:133]
	v_ashrrev_i32_e32 v251, 5, v135
	v_mad_u32_u24 v252, v251, s89, v134
	ds_read_b128 v[206:209], v252
	v_add_u32_e32 v250, 0x200, v135
	v_ashrrev_i32_e32 v251, 5, v250
	v_mad_u32_u24 v252, v251, s89, v134
	ds_read_b128 v[210:213], v252
	v_add_u32_e32 v250, 0x400, v135
	v_ashrrev_i32_e32 v251, 5, v250
	v_mad_u32_u24 v252, v251, s89, v134
	ds_read_b128 v[214:217], v252
	v_add_u32_e32 v250, 0x600, v135
	v_ashrrev_i32_e32 v251, 5, v250
	v_mad_u32_u24 v252, v251, s89, v134
	ds_read_b128 v[218:221], v252
	v_add_u32_e32 v250, 0x800, v135
	v_ashrrev_i32_e32 v251, 5, v250
	v_mad_u32_u24 v252, v251, s89, v134
	ds_read_b128 v[222:225], v252
	v_add_u32_e32 v250, 0xa00, v135
	v_ashrrev_i32_e32 v251, 5, v250
	v_mad_u32_u24 v252, v251, s89, v134
	ds_read_b128 v[226:229], v252
	v_add_u32_e32 v250, 0xc00, v135
	v_ashrrev_i32_e32 v251, 5, v250
	v_mad_u32_u24 v252, v251, s89, v134
	ds_read_b128 v[230:233], v252
	v_add_u32_e32 v250, 0xe00, v135
	v_ashrrev_i32_e32 v251, 5, v250
	v_mad_u32_u24 v252, v251, s89, v134
	ds_read_b128 v[234:237], v252
	v_ashrrev_i32_e32 v251, 5, v135
	v_add_u32_e32 v252, s97, v251
	v_ashrrev_i32_e32 v253, 31, v252
	v_lshlrev_b64 v[252:253], 11, v[252:253]
	v_lshl_add_u64 v[252:253], v[68:69], 0, v[252:253]
	s_waitcnt lgkmcnt(7)
	global_store_dwordx4 v[252:253], v[206:209], off
	v_add_u32_e32 v250, 0x200, v135
	v_ashrrev_i32_e32 v251, 5, v250
	v_add_u32_e32 v252, s97, v251
	v_ashrrev_i32_e32 v253, 31, v252
	v_lshlrev_b64 v[252:253], 11, v[252:253]
	v_lshl_add_u64 v[252:253], v[68:69], 0, v[252:253]
	s_waitcnt lgkmcnt(6)
	global_store_dwordx4 v[252:253], v[210:213], off
	v_add_u32_e32 v250, 0x400, v135
	v_ashrrev_i32_e32 v251, 5, v250
	v_add_u32_e32 v252, s97, v251
	v_ashrrev_i32_e32 v253, 31, v252
	v_lshlrev_b64 v[252:253], 11, v[252:253]
	v_lshl_add_u64 v[252:253], v[68:69], 0, v[252:253]
	s_waitcnt lgkmcnt(5)
	global_store_dwordx4 v[252:253], v[214:217], off
	v_add_u32_e32 v250, 0x600, v135
	v_ashrrev_i32_e32 v251, 5, v250
	v_add_u32_e32 v252, s97, v251
	v_ashrrev_i32_e32 v253, 31, v252
	v_lshlrev_b64 v[252:253], 11, v[252:253]
	v_lshl_add_u64 v[252:253], v[68:69], 0, v[252:253]
	s_waitcnt lgkmcnt(4)
	global_store_dwordx4 v[252:253], v[218:221], off
	v_add_u32_e32 v250, 0x800, v135
	v_ashrrev_i32_e32 v251, 5, v250
	v_add_u32_e32 v252, s97, v251
	v_ashrrev_i32_e32 v253, 31, v252
	v_lshlrev_b64 v[252:253], 11, v[252:253]
	v_lshl_add_u64 v[252:253], v[68:69], 0, v[252:253]
	s_waitcnt lgkmcnt(3)
	global_store_dwordx4 v[252:253], v[222:225], off
	v_add_u32_e32 v250, 0xa00, v135
	v_ashrrev_i32_e32 v251, 5, v250
	v_add_u32_e32 v252, s97, v251
	v_ashrrev_i32_e32 v253, 31, v252
	v_lshlrev_b64 v[252:253], 11, v[252:253]
	v_lshl_add_u64 v[252:253], v[68:69], 0, v[252:253]
	s_waitcnt lgkmcnt(2)
	global_store_dwordx4 v[252:253], v[226:229], off
	v_add_u32_e32 v250, 0xc00, v135
	v_ashrrev_i32_e32 v251, 5, v250
	v_add_u32_e32 v252, s97, v251
	v_ashrrev_i32_e32 v253, 31, v252
	v_lshlrev_b64 v[252:253], 11, v[252:253]
	v_lshl_add_u64 v[252:253], v[68:69], 0, v[252:253]
	s_waitcnt lgkmcnt(1)
	global_store_dwordx4 v[252:253], v[230:233], off
	v_add_u32_e32 v250, 0xe00, v135
	v_ashrrev_i32_e32 v251, 5, v250
	v_add_u32_e32 v252, s97, v251
	v_ashrrev_i32_e32 v253, 31, v252
	v_lshlrev_b64 v[252:253], 11, v[252:253]
	v_lshl_add_u64 v[252:253], v[68:69], 0, v[252:253]
	s_waitcnt lgkmcnt(0)
	global_store_dwordx4 v[252:253], v[234:237], off
	v_mov_b32_e32 v70, v137
	s_and_b64 vcc, exec, s[28:29]
	s_cbranch_vccz .LBB0_193
	v_xor_b32_e32 v246, 1, v188
	v_lshlrev_b32_e32 v246, 2, v246
	v_xor_b32_e32 v247, 2, v188
	v_lshlrev_b32_e32 v247, 2, v247
	v_xor_b32_e32 v248, 4, v188
	v_lshlrev_b32_e32 v248, 2, v248
	v_xor_b32_e32 v249, 8, v188
	v_lshlrev_b32_e32 v249, 2, v249
	v_lshlrev_b32_e32 v251, 16, v207
	v_lshlrev_b32_e32 v250, 16, v206
	v_and_b32_e32 v207, 0xffff0000, v207
	v_and_b32_e32 v206, 0xffff0000, v206
	v_pk_mul_f32 v[206:207], v[206:207], v[206:207]
	s_nop 0
	v_pk_fma_f32 v[206:207], v[250:251], v[250:251], v[206:207]
	v_lshlrev_b32_e32 v251, 16, v209
	v_lshlrev_b32_e32 v250, 16, v208
	v_and_b32_e32 v209, 0xffff0000, v209
	v_and_b32_e32 v208, 0xffff0000, v208
	v_pk_mul_f32 v[208:209], v[208:209], v[208:209]
	s_nop 0
	v_pk_fma_f32 v[208:209], v[250:251], v[250:251], v[208:209]
	v_add_f32_e32 v206, v206, v207
	v_add_f32_e32 v206, v208, v206
	v_add_f32_e32 v206, v209, v206
	v_lshlrev_b32_e32 v251, 16, v211
	v_lshlrev_b32_e32 v250, 16, v210
	v_and_b32_e32 v211, 0xffff0000, v211
	v_and_b32_e32 v210, 0xffff0000, v210
	v_pk_mul_f32 v[210:211], v[210:211], v[210:211]
	s_nop 0
	v_pk_fma_f32 v[210:211], v[250:251], v[250:251], v[210:211]
	v_lshlrev_b32_e32 v251, 16, v213
	v_lshlrev_b32_e32 v250, 16, v212
	v_and_b32_e32 v213, 0xffff0000, v213
	v_and_b32_e32 v212, 0xffff0000, v212
	v_pk_mul_f32 v[212:213], v[212:213], v[212:213]
	s_nop 0
	v_pk_fma_f32 v[212:213], v[250:251], v[250:251], v[212:213]
	v_add_f32_e32 v210, v210, v211
	v_add_f32_e32 v210, v212, v210
	v_add_f32_e32 v210, v213, v210
	v_lshlrev_b32_e32 v251, 16, v215
	v_lshlrev_b32_e32 v250, 16, v214
	v_and_b32_e32 v215, 0xffff0000, v215
	v_and_b32_e32 v214, 0xffff0000, v214
	v_pk_mul_f32 v[214:215], v[214:215], v[214:215]
	s_nop 0
	v_pk_fma_f32 v[214:215], v[250:251], v[250:251], v[214:215]
	v_lshlrev_b32_e32 v251, 16, v217
	v_lshlrev_b32_e32 v250, 16, v216
	v_and_b32_e32 v217, 0xffff0000, v217
	v_and_b32_e32 v216, 0xffff0000, v216
	v_pk_mul_f32 v[216:217], v[216:217], v[216:217]
	s_nop 0
	v_pk_fma_f32 v[216:217], v[250:251], v[250:251], v[216:217]
	v_add_f32_e32 v214, v214, v215
	v_add_f32_e32 v214, v216, v214
	v_add_f32_e32 v214, v217, v214
	v_lshlrev_b32_e32 v251, 16, v219
	v_lshlrev_b32_e32 v250, 16, v218
	v_and_b32_e32 v219, 0xffff0000, v219
	v_and_b32_e32 v218, 0xffff0000, v218
	v_pk_mul_f32 v[218:219], v[218:219], v[218:219]
	s_nop 0
	v_pk_fma_f32 v[218:219], v[250:251], v[250:251], v[218:219]
	v_lshlrev_b32_e32 v251, 16, v221
	v_lshlrev_b32_e32 v250, 16, v220
	v_and_b32_e32 v221, 0xffff0000, v221
	v_and_b32_e32 v220, 0xffff0000, v220
	v_pk_mul_f32 v[220:221], v[220:221], v[220:221]
	s_nop 0
	v_pk_fma_f32 v[220:221], v[250:251], v[250:251], v[220:221]
	v_add_f32_e32 v218, v218, v219
	v_add_f32_e32 v218, v220, v218
	v_add_f32_e32 v218, v221, v218
	v_lshlrev_b32_e32 v251, 16, v223
	v_lshlrev_b32_e32 v250, 16, v222
	v_and_b32_e32 v223, 0xffff0000, v223
	v_and_b32_e32 v222, 0xffff0000, v222
	v_pk_mul_f32 v[222:223], v[222:223], v[222:223]
	s_nop 0
	v_pk_fma_f32 v[222:223], v[250:251], v[250:251], v[222:223]
	v_lshlrev_b32_e32 v251, 16, v225
	v_lshlrev_b32_e32 v250, 16, v224
	v_and_b32_e32 v225, 0xffff0000, v225
	v_and_b32_e32 v224, 0xffff0000, v224
	v_pk_mul_f32 v[224:225], v[224:225], v[224:225]
	s_nop 0
	v_pk_fma_f32 v[224:225], v[250:251], v[250:251], v[224:225]
	v_add_f32_e32 v222, v222, v223
	v_add_f32_e32 v222, v224, v222
	v_add_f32_e32 v222, v225, v222
	v_lshlrev_b32_e32 v251, 16, v227
	v_lshlrev_b32_e32 v250, 16, v226
	v_and_b32_e32 v227, 0xffff0000, v227
	v_and_b32_e32 v226, 0xffff0000, v226
	v_pk_mul_f32 v[226:227], v[226:227], v[226:227]
	s_nop 0
	v_pk_fma_f32 v[226:227], v[250:251], v[250:251], v[226:227]
	v_lshlrev_b32_e32 v251, 16, v229
	v_lshlrev_b32_e32 v250, 16, v228
	v_and_b32_e32 v229, 0xffff0000, v229
	v_and_b32_e32 v228, 0xffff0000, v228
	v_pk_mul_f32 v[228:229], v[228:229], v[228:229]
	s_nop 0
	v_pk_fma_f32 v[228:229], v[250:251], v[250:251], v[228:229]
	v_add_f32_e32 v226, v226, v227
	v_add_f32_e32 v226, v228, v226
	v_add_f32_e32 v226, v229, v226
	v_lshlrev_b32_e32 v251, 16, v231
	v_lshlrev_b32_e32 v250, 16, v230
	v_and_b32_e32 v231, 0xffff0000, v231
	v_and_b32_e32 v230, 0xffff0000, v230
	v_pk_mul_f32 v[230:231], v[230:231], v[230:231]
	s_nop 0
	v_pk_fma_f32 v[230:231], v[250:251], v[250:251], v[230:231]
	v_lshlrev_b32_e32 v251, 16, v233
	v_lshlrev_b32_e32 v250, 16, v232
	v_and_b32_e32 v233, 0xffff0000, v233
	v_and_b32_e32 v232, 0xffff0000, v232
	v_pk_mul_f32 v[232:233], v[232:233], v[232:233]
	s_nop 0
	v_pk_fma_f32 v[232:233], v[250:251], v[250:251], v[232:233]
	v_add_f32_e32 v230, v230, v231
	v_add_f32_e32 v230, v232, v230
	v_add_f32_e32 v230, v233, v230
	v_lshlrev_b32_e32 v251, 16, v235
	v_lshlrev_b32_e32 v250, 16, v234
	v_and_b32_e32 v235, 0xffff0000, v235
	v_and_b32_e32 v234, 0xffff0000, v234
	v_pk_mul_f32 v[234:235], v[234:235], v[234:235]
	s_nop 0
	v_pk_fma_f32 v[234:235], v[250:251], v[250:251], v[234:235]
	v_lshlrev_b32_e32 v251, 16, v237
	v_lshlrev_b32_e32 v250, 16, v236
	v_and_b32_e32 v237, 0xffff0000, v237
	v_and_b32_e32 v236, 0xffff0000, v236
	v_pk_mul_f32 v[236:237], v[236:237], v[236:237]
	s_nop 0
	v_pk_fma_f32 v[236:237], v[250:251], v[250:251], v[236:237]
	v_add_f32_e32 v234, v234, v235
	v_add_f32_e32 v234, v236, v234
	v_add_f32_e32 v234, v237, v234
	ds_bpermute_b32 v238, v246, v206
	ds_bpermute_b32 v239, v246, v210
	ds_bpermute_b32 v240, v246, v214
	ds_bpermute_b32 v241, v246, v218
	ds_bpermute_b32 v242, v246, v222
	ds_bpermute_b32 v243, v246, v226
	ds_bpermute_b32 v244, v246, v230
	ds_bpermute_b32 v245, v246, v234
	s_waitcnt lgkmcnt(7)
	v_add_f32_e32 v206, v206, v238
	s_waitcnt lgkmcnt(6)
	v_add_f32_e32 v210, v210, v239
	s_waitcnt lgkmcnt(5)
	v_add_f32_e32 v214, v214, v240
	s_waitcnt lgkmcnt(4)
	v_add_f32_e32 v218, v218, v241
	s_waitcnt lgkmcnt(3)
	v_add_f32_e32 v222, v222, v242
	s_waitcnt lgkmcnt(2)
	v_add_f32_e32 v226, v226, v243
	s_waitcnt lgkmcnt(1)
	v_add_f32_e32 v230, v230, v244
	s_waitcnt lgkmcnt(0)
	v_add_f32_e32 v234, v234, v245
	ds_bpermute_b32 v238, v247, v206
	ds_bpermute_b32 v239, v247, v210
	ds_bpermute_b32 v240, v247, v214
	ds_bpermute_b32 v241, v247, v218
	ds_bpermute_b32 v242, v247, v222
	ds_bpermute_b32 v243, v247, v226
	ds_bpermute_b32 v244, v247, v230
	ds_bpermute_b32 v245, v247, v234
	s_waitcnt lgkmcnt(7)
	v_add_f32_e32 v206, v206, v238
	s_waitcnt lgkmcnt(6)
	v_add_f32_e32 v210, v210, v239
	s_waitcnt lgkmcnt(5)
	v_add_f32_e32 v214, v214, v240
	s_waitcnt lgkmcnt(4)
	v_add_f32_e32 v218, v218, v241
	s_waitcnt lgkmcnt(3)
	v_add_f32_e32 v222, v222, v242
	s_waitcnt lgkmcnt(2)
	v_add_f32_e32 v226, v226, v243
	s_waitcnt lgkmcnt(1)
	v_add_f32_e32 v230, v230, v244
	s_waitcnt lgkmcnt(0)
	v_add_f32_e32 v234, v234, v245
	ds_bpermute_b32 v238, v248, v206
	ds_bpermute_b32 v239, v248, v210
	ds_bpermute_b32 v240, v248, v214
	ds_bpermute_b32 v241, v248, v218
	ds_bpermute_b32 v242, v248, v222
	ds_bpermute_b32 v243, v248, v226
	ds_bpermute_b32 v244, v248, v230
	ds_bpermute_b32 v245, v248, v234
	s_waitcnt lgkmcnt(7)
	v_add_f32_e32 v206, v206, v238
	s_waitcnt lgkmcnt(6)
	v_add_f32_e32 v210, v210, v239
	s_waitcnt lgkmcnt(5)
	v_add_f32_e32 v214, v214, v240
	s_waitcnt lgkmcnt(4)
	v_add_f32_e32 v218, v218, v241
	s_waitcnt lgkmcnt(3)
	v_add_f32_e32 v222, v222, v242
	s_waitcnt lgkmcnt(2)
	v_add_f32_e32 v226, v226, v243
	s_waitcnt lgkmcnt(1)
	v_add_f32_e32 v230, v230, v244
	s_waitcnt lgkmcnt(0)
	v_add_f32_e32 v234, v234, v245
	ds_bpermute_b32 v238, v249, v206
	ds_bpermute_b32 v239, v249, v210
	ds_bpermute_b32 v240, v249, v214
	ds_bpermute_b32 v241, v249, v218
	ds_bpermute_b32 v242, v249, v222
	ds_bpermute_b32 v243, v249, v226
	ds_bpermute_b32 v244, v249, v230
	ds_bpermute_b32 v245, v249, v234
	s_waitcnt lgkmcnt(7)
	v_add_f32_e32 v206, v206, v238
	s_waitcnt lgkmcnt(6)
	v_add_f32_e32 v210, v210, v239
	s_waitcnt lgkmcnt(5)
	v_add_f32_e32 v214, v214, v240
	s_waitcnt lgkmcnt(4)
	v_add_f32_e32 v218, v218, v241
	s_waitcnt lgkmcnt(3)
	v_add_f32_e32 v222, v222, v242
	s_waitcnt lgkmcnt(2)
	v_add_f32_e32 v226, v226, v243
	s_waitcnt lgkmcnt(1)
	v_add_f32_e32 v230, v230, v244
	s_waitcnt lgkmcnt(0)
	v_add_f32_e32 v234, v234, v245
	v_max_f32_e32 v250, v137, v137
	v_max_f32_e32 v70, v250, v206
	v_max_f32_e32 v250, v70, v70
	v_max_f32_e32 v70, v250, v210
	v_max_f32_e32 v250, v70, v70
	v_max_f32_e32 v70, v250, v214
	v_max_f32_e32 v250, v70, v70
	v_max_f32_e32 v70, v250, v218
	v_max_f32_e32 v250, v70, v70
	v_max_f32_e32 v70, v250, v222
	v_max_f32_e32 v250, v70, v70
	v_max_f32_e32 v70, v250, v226
	v_max_f32_e32 v250, v70, v70
	v_max_f32_e32 v70, v250, v230
	v_max_f32_e32 v250, v70, v70
	v_max_f32_e32 v70, v250, v234
